# attention k-tile loop: LDS fragment reads software-pipelined 4 deep via ring registers (QK and PV), plus fixup rewrite
# speedup vs baseline: 1.0036x; 1.0014x over previous
; __device__ __forceinline__ void lds_barrier() { asm volatile("s_waitcnt lgkmcnt(0)\n\ts_barrier" ::: "memory"); }
; __device__ void attn_phase(const Params& p, unsigned char* ldsb) {
;     ...
;             lds_barrier();
;             f32x4 S[4][2];
; #pragma unroll
;             for (int kp = 0; kp < 4; ++kp)
; #pragma unroll
;                 for (int qt = 0; qt < 2; ++qt) { const float* bp = Bt + g * BT_LD + (kb + 4 * fq - qtok[qt] + 192) + 16 * kp;
;                     S[kp][qt] = (f32x4){bp[0], bp[1], bp[2], bp[3]}; }
; #pragma unroll
;             for (int ks = 0; ks < 4; ++ks)
; #pragma unroll
;                 for (int kp = 0; kp < 4; ++kp) { const f16x8 Kf = *(const f16x8*)(Ks + (16 * kp + fr) * KS_LD + 32 * ks + 8 * fq);
;                     S[kp][0] = __builtin_amdgcn_mfma_f32_16x16x32_f16(Kf, Qf[0][ks], S[kp][0], 0, 0, 0);
;                     S[kp][1] = __builtin_amdgcn_mfma_f32_16x16x32_f16(Kf, Qf[1][ks], S[kp][1], 0, 0, 0); }
;             f16x8 Pf[2][2];
; #pragma unroll
;             for (int qt = 0; qt < 2; ++qt) {
;                 float tmax = -3.0e38f;
; #pragma unroll
;                 for (int kp = 0; kp < 4; ++kp)
; #pragma unroll
;                     for (int r = 0; r < 4; ++r) tmax = fmaxf(tmax, S[kp][qt][r]);
;                 if (__builtin_amdgcn_ballot_w64(tmax > mrun[qt] + 8.0f) != 0ull) {
;                     tmax = fmaxf(tmax, __shfl_xor(tmax, 16)); tmax = fmaxf(tmax, __shfl_xor(tmax, 32));
;                     const float mnew = fmaxf(mrun[qt], tmax), alpha = __builtin_amdgcn_exp2f(mrun[qt] - mnew); mrun[qt] = mnew; lrun[qt] *= alpha;
; #pragma unroll
;                     for (int dt = 0; dt < 8; ++dt) Oa[dt][qt] *= alpha;
;                 }
.LBB0_252:
	s_and_b32 s12, s11, 1
	s_mul_i32 s13, s12, 0x8c00
	s_add_i32 s13, s13, 0
	s_waitcnt lgkmcnt(0)
	s_barrier
	v_add3_u32 v162, s13, v148, v185
	ds_read2_b32 v[116:117], v193 offset0:16 offset1:17
	ds_read2_b32 v[118:119], v193 offset0:18 offset1:19
	ds_read2_b32 v[120:121], v193 offset1:1
	ds_read2_b32 v[122:123], v193 offset0:2 offset1:3
	ds_read2_b32 v[124:125], v193 offset0:32 offset1:33
	ds_read2_b32 v[126:127], v193 offset0:34 offset1:35
	ds_read2_b32 v[128:129], v193 offset0:48 offset1:49
	ds_read2_b32 v[130:131], v193 offset0:50 offset1:51
	ds_read2_b32 v[132:133], v193 offset0:64 offset1:65
	ds_read2_b32 v[134:135], v193 offset0:66 offset1:67
	ds_read_b128 v[234:237], v162
	ds_read_b128 v[238:241], v162 offset:4352
	ds_read_b128 v[242:245], v162 offset:8704
	ds_read_b128 v[246:249], v162 offset:13056
	s_waitcnt lgkmcnt(3)
	ds_read_b128 v[226:229], v162 offset:64
	v_mfma_f32_16x16x32_f16 v[140:143], v[234:237], v[36:39], v[116:119]
	v_mfma_f32_16x16x32_f16 v[120:123], v[234:237], v[52:55], v[120:123]
	s_waitcnt lgkmcnt(3)
	ds_read_b128 v[234:237], v162 offset:4416
	v_mfma_f32_16x16x32_f16 v[144:147], v[238:241], v[36:39], v[124:127]
	v_mfma_f32_16x16x32_f16 v[116:119], v[238:241], v[52:55], v[116:119]
	s_waitcnt lgkmcnt(3)
	ds_read_b128 v[238:241], v162 offset:8768
	v_mfma_f32_16x16x32_f16 v[196:199], v[242:245], v[36:39], v[128:131]
	v_mfma_f32_16x16x32_f16 v[124:127], v[242:245], v[52:55], v[124:127]
	s_waitcnt lgkmcnt(3)
	ds_read_b128 v[242:245], v162 offset:13120
	v_mfma_f32_16x16x32_f16 v[132:135], v[246:249], v[36:39], v[132:135]
	v_mfma_f32_16x16x32_f16 v[128:131], v[246:249], v[52:55], v[128:131]
	s_waitcnt lgkmcnt(3)
	ds_read_b128 v[246:249], v162 offset:128
	v_mfma_f32_16x16x32_f16 v[140:143], v[226:229], v[40:43], v[140:143]
	v_mfma_f32_16x16x32_f16 v[120:123], v[226:229], v[56:59], v[120:123]
	s_waitcnt lgkmcnt(3)
	ds_read_b128 v[226:229], v162 offset:4480
	v_mfma_f32_16x16x32_f16 v[144:147], v[234:237], v[40:43], v[144:147]
	v_mfma_f32_16x16x32_f16 v[116:119], v[234:237], v[56:59], v[116:119]
	s_waitcnt lgkmcnt(3)
	ds_read_b128 v[234:237], v162 offset:8832
	v_mfma_f32_16x16x32_f16 v[196:199], v[238:241], v[40:43], v[196:199]
	v_mfma_f32_16x16x32_f16 v[124:127], v[238:241], v[56:59], v[124:127]
	s_waitcnt lgkmcnt(3)
	ds_read_b128 v[238:241], v162 offset:13184
	v_mfma_f32_16x16x32_f16 v[132:135], v[242:245], v[40:43], v[132:135]
	v_mfma_f32_16x16x32_f16 v[128:131], v[242:245], v[56:59], v[128:131]
	s_waitcnt lgkmcnt(3)
	ds_read_b128 v[242:245], v162 offset:192
	v_mfma_f32_16x16x32_f16 v[140:143], v[246:249], v[44:47], v[140:143]
	v_mfma_f32_16x16x32_f16 v[120:123], v[246:249], v[60:63], v[120:123]
	s_waitcnt lgkmcnt(3)
	ds_read_b128 v[246:249], v162 offset:4544
	v_mfma_f32_16x16x32_f16 v[144:147], v[226:229], v[44:47], v[144:147]
	v_mfma_f32_16x16x32_f16 v[200:203], v[226:229], v[60:63], v[116:119]
	s_waitcnt lgkmcnt(3)
	ds_read_b128 v[226:229], v162 offset:8896
	v_mfma_f32_16x16x32_f16 v[196:199], v[234:237], v[44:47], v[196:199]
	v_mfma_f32_16x16x32_f16 v[204:207], v[234:237], v[60:63], v[124:127]
	s_waitcnt lgkmcnt(3)
	ds_read_b128 v[234:237], v162 offset:13248
	v_mfma_f32_16x16x32_f16 v[208:211], v[238:241], v[44:47], v[132:135]
	v_mfma_f32_16x16x32_f16 v[212:215], v[238:241], v[60:63], v[128:131]
	s_waitcnt lgkmcnt(3)
	v_mfma_f32_16x16x32_f16 v[132:135], v[242:245], v[48:51], v[140:143]
	v_mfma_f32_16x16x32_f16 v[116:119], v[242:245], v[64:67], v[120:123]
	s_waitcnt lgkmcnt(2)
	v_mfma_f32_16x16x32_f16 v[136:139], v[246:249], v[48:51], v[144:147]
	v_mfma_f32_16x16x32_f16 v[124:127], v[246:249], v[64:67], v[200:203]
	s_waitcnt lgkmcnt(1)
	v_mfma_f32_16x16x32_f16 v[140:143], v[226:229], v[48:51], v[196:199]
	v_mfma_f32_16x16x32_f16 v[128:131], v[226:229], v[64:67], v[204:207]
	s_nop 0
	v_max3_f32 v162, v132, s67, v133
	v_max3_f32 v162, v162, v134, v135
	s_waitcnt lgkmcnt(0)
	v_mfma_f32_16x16x32_f16 v[144:147], v[234:237], v[48:51], v[208:211]
	v_max3_f32 v162, v162, v136, v137
	v_max3_f32 v162, v162, v138, v139
	v_max3_f32 v162, v162, v140, v141
	v_mfma_f32_16x16x32_f16 v[120:123], v[234:237], v[64:67], v[212:215]
	v_max3_f32 v162, v162, v142, v143
	s_nop 2
	v_max3_f32 v162, v162, v144, v145
	v_max3_f32 v195, v162, v146, v147
	v_add_f32_e32 v162, 0x41000000, v3
	v_cmp_gt_f32_e32 vcc, v195, v162
	s_cbranch_vccz .LBB0_254
	v_and_b32_e32 v163, 64, v221
	v_xor_b32_e32 v162, 16, v221
	v_add_u32_e32 v163, 64, v163
	v_cmp_lt_i32_e32 vcc, v162, v163
	v_max_f32_e32 v164, v195, v195
	s_nop 0
	v_cndmask_b32_e32 v162, v221, v162, vcc
	v_lshlrev_b32_e32 v162, 2, v162
	ds_bpermute_b32 v162, v162, v195
	s_waitcnt lgkmcnt(0)
	v_max_f32_e32 v162, v162, v162
	v_max_f32_e32 v162, v164, v162
	v_xor_b32_e32 v164, 32, v221
	v_cmp_lt_i32_e32 vcc, v164, v163
	s_nop 1
	v_cndmask_b32_e32 v163, v221, v164, vcc
	v_lshlrev_b32_e32 v163, 2, v163
	ds_bpermute_b32 v163, v163, v162
	s_waitcnt lgkmcnt(0)
	v_max3_f32 v163, v3, v162, v163
	v_sub_f32_e32 v3, v3, v163
	v_exp_f32_e32 v162, v3
	v_mov_b32_e32 v3, v163
	v_mul_f32_e32 v2, v2, v162
	v_pk_mul_f32 v[94:95], v[94:95], v[162:163] op_sel_hi:[1,0]
	v_pk_mul_f32 v[92:93], v[92:93], v[162:163] op_sel_hi:[1,0]
	v_pk_mul_f32 v[82:83], v[82:83], v[162:163] op_sel_hi:[1,0]
	v_pk_mul_f32 v[80:81], v[80:81], v[162:163] op_sel_hi:[1,0]
	v_pk_mul_f32 v[78:79], v[78:79], v[162:163] op_sel_hi:[1,0]
	v_pk_mul_f32 v[76:77], v[76:77], v[162:163] op_sel_hi:[1,0]
	v_pk_mul_f32 v[74:75], v[74:75], v[162:163] op_sel_hi:[1,0]
	v_pk_mul_f32 v[72:73], v[72:73], v[162:163] op_sel_hi:[1,0]
	v_pk_mul_f32 v[70:71], v[70:71], v[162:163] op_sel_hi:[1,0]
	v_pk_mul_f32 v[68:69], v[68:69], v[162:163] op_sel_hi:[1,0]
	v_pk_mul_f32 v[98:99], v[98:99], v[162:163] op_sel_hi:[1,0]
	v_pk_mul_f32 v[96:97], v[96:97], v[162:163] op_sel_hi:[1,0]
	v_pk_mul_f32 v[90:91], v[90:91], v[162:163] op_sel_hi:[1,0]
	v_pk_mul_f32 v[88:89], v[88:89], v[162:163] op_sel_hi:[1,0]
	v_pk_mul_f32 v[86:87], v[86:87], v[162:163] op_sel_hi:[1,0]
	v_pk_mul_f32 v[84:85], v[84:85], v[162:163] op_sel_hi:[1,0]

; __device__ void attn_phase(const Params& p, unsigned char* ldsb) {
;     ...
;                 const float mref = mrun[qt];
;                 float ls = 0.f;
; #pragma unroll
;                 for (int kp = 0; kp < 4; ++kp)
; #pragma unroll
;                     for (int r = 0; r < 4; ++r) { const float pe = __builtin_amdgcn_exp2f(S[kp][qt][r] - mref); S[kp][qt][r] = pe; ls += pe; }
;                 lrun[qt] += ls;
; #pragma unroll
;                 for (int i = 0; i < 2; ++i) { f16x8 pf;
; #pragma unroll
;                     for (int j = 0; j < 4; ++j) { pf[j] = (h16)S[2 * i][qt][j]; pf[4 + j] = (h16)S[2 * i + 1][qt][j]; }
;                     Pf[i][qt] = pf; }
;             }
; #pragma unroll
;             for (int dt = 0; dt < 8; ++dt)
; #pragma unroll
;                 for (int i = 0; i < 2; ++i) {
;                     const f16x4 va = *(const f16x4*)(Vs + (16 * dt + fr) * VS_LD + 32 * i + 4 * fq), vb = *(const f16x4*)(Vs + (16 * dt + fr) * VS_LD + 32 * i + 16 + 4 * fq);
;                     const f16x8 Vf = __builtin_shufflevector(va, vb, 0, 1, 2, 3, 4, 5, 6, 7);
;                     Oa[dt][0] = __builtin_amdgcn_mfma_f32_16x16x32_f16(Vf, Pf[i][0], Oa[dt][0], 0, 0, 0);
;                     Oa[dt][1] = __builtin_amdgcn_mfma_f32_16x16x32_f16(Vf, Pf[i][1], Oa[dt][1], 0, 0, 0); }
;             if (kt < kt_hi) { h16* Kw = (h16*)(ldsb + (cur ^ 1) * KVB); h16* Vw = Kw + 64 * KS_LD;
;                 *(u32x4*)(Kw + kkey * KS_LD + kdc) = pk0; *(u32x4*)(Kw + (kkey + 32) * KS_LD + kdc) = pk1;
;                 *(u32x4*)(Vw + vd * VS_LD + vkc) = pv0; *(u32x4*)(Vw + (vd + 64) * VS_LD + vkc) = pv1; }
.LBB0_256:
	v_add3_u32 v162, s13, v186, v191
	v_add_u32_e32 v163, 0x4000, v162
	ds_read2_b64 v[204:207], v163 offset0:128 offset1:132
	v_sub_f32_e32 v132, v132, v3
	v_sub_f32_e32 v133, v133, v3
	v_sub_f32_e32 v134, v134, v3
	v_sub_f32_e32 v135, v135, v3
	v_sub_f32_e32 v136, v136, v3
	v_sub_f32_e32 v137, v137, v3
	v_sub_f32_e32 v138, v138, v3
	v_sub_f32_e32 v139, v139, v3
	v_sub_f32_e32 v116, v116, v194
	v_sub_f32_e32 v117, v117, v194
	v_sub_f32_e32 v118, v118, v194
	v_sub_f32_e32 v119, v119, v194
	v_sub_f32_e32 v124, v124, v194
	v_sub_f32_e32 v125, v125, v194
	v_sub_f32_e32 v126, v126, v194
	v_sub_f32_e32 v127, v127, v194
	v_exp_f32_e32 v132, v132
	v_exp_f32_e32 v133, v133
	v_exp_f32_e32 v134, v134
	v_exp_f32_e32 v135, v135
	v_exp_f32_e32 v136, v136
	v_exp_f32_e32 v137, v137
	v_exp_f32_e32 v138, v138
	v_exp_f32_e32 v139, v139
	v_exp_f32_e32 v116, v116
	v_exp_f32_e32 v117, v117
	v_exp_f32_e32 v118, v118
	v_exp_f32_e32 v119, v119
	v_exp_f32_e32 v124, v124
	v_exp_f32_e32 v125, v125
	v_exp_f32_e32 v126, v126
	v_exp_f32_e32 v127, v127
	ds_read2_b64 v[212:215], v163 offset0:136 offset1:140
	v_sub_f32_e32 v140, v140, v3
	v_sub_f32_e32 v141, v141, v3
	v_sub_f32_e32 v142, v142, v3
	v_sub_f32_e32 v143, v143, v3
	v_sub_f32_e32 v144, v144, v3
	v_sub_f32_e32 v145, v145, v3
	v_sub_f32_e32 v146, v146, v3
	v_sub_f32_e32 v147, v147, v3
	v_sub_f32_e32 v128, v128, v194
	v_sub_f32_e32 v129, v129, v194
	v_sub_f32_e32 v130, v130, v194
	v_sub_f32_e32 v131, v131, v194
	v_sub_f32_e32 v120, v120, v194
	v_sub_f32_e32 v164, v121, v194
	v_sub_f32_e32 v121, v122, v194
	v_sub_f32_e32 v122, v123, v194
	v_exp_f32_e32 v140, v140
	v_exp_f32_e32 v141, v141
	v_exp_f32_e32 v142, v142
	v_exp_f32_e32 v143, v143
	v_exp_f32_e32 v144, v144
	v_exp_f32_e32 v145, v145
	v_exp_f32_e32 v146, v146
	v_exp_f32_e32 v147, v147
	v_cvt_pk_f16_f32 v199, v138, v139
	v_cvt_pk_f16_f32 v198, v136, v137
	v_cvt_pk_f16_f32 v197, v134, v135
	v_cvt_pk_f16_f32 v196, v132, v133
	v_exp_f32_e32 v128, v128
	v_exp_f32_e32 v129, v129
	v_exp_f32_e32 v130, v130
	v_exp_f32_e32 v120, v120
	v_exp_f32_e32 v121, v121
	v_exp_f32_e32 v122, v122
	v_cvt_pk_f16_f32 v211, v126, v127
	v_cvt_pk_f16_f32 v210, v124, v125
	v_cvt_pk_f16_f32 v209, v118, v119
	v_cvt_pk_f16_f32 v208, v116, v117
	v_exp_f32_e32 v123, v164
	v_exp_f32_e32 v131, v131
	v_add3_u32 v222, s13, v187, v191
	v_add_u32_e32 v222, 0x4000, v222
	ds_read2_b64 v[234:237], v222 offset0:128 offset1:132
	ds_read2_b64 v[238:241], v222 offset0:136 offset1:140
	v_add3_u32 v223, s13, v188, v191
	v_add_u32_e32 v223, 0x4000, v223
	ds_read2_b64 v[242:245], v223 offset0:128 offset1:132
	s_waitcnt lgkmcnt(4)
	v_mfma_f32_16x16x32_f16 v[92:95], v[204:207], v[196:199], v[92:95]
	v_cvt_pk_f16_f32 v203, v146, v147
	v_cvt_pk_f16_f32 v202, v144, v145
	v_mfma_f32_16x16x32_f16 v[20:23], v[204:207], v[208:211], v[20:23]
	v_cvt_pk_f16_f32 v201, v142, v143
	v_cvt_pk_f16_f32 v200, v140, v141
	v_cvt_pk_f16_f32 v207, v121, v122
	v_cvt_pk_f16_f32 v206, v120, v123
	v_cvt_pk_f16_f32 v205, v130, v131
	v_cvt_pk_f16_f32 v204, v128, v129
	ds_read2_b64 v[246:249], v223 offset0:136 offset1:140
	s_waitcnt lgkmcnt(4)
	v_mfma_f32_16x16x32_f16 v[92:95], v[212:215], v[200:203], v[92:95]
	s_andn2_b64 vcc, exec, s[0:1]
	v_mfma_f32_16x16x32_f16 v[20:23], v[212:215], v[204:207], v[20:23]
	v_add3_u32 v224, s13, v189, v191
	v_add_u32_e32 v224, 0x4000, v224
	ds_read2_b64 v[226:229], v224 offset0:128 offset1:132
	s_waitcnt lgkmcnt(4)
	v_mfma_f32_16x16x32_f16 v[80:83], v[234:237], v[196:199], v[80:83]
	v_mfma_f32_16x16x32_f16 v[16:19], v[234:237], v[208:211], v[16:19]
	ds_read2_b64 v[234:237], v224 offset0:136 offset1:140
	s_waitcnt lgkmcnt(4)
	v_mfma_f32_16x16x32_f16 v[80:83], v[238:241], v[200:203], v[80:83]
	v_mfma_f32_16x16x32_f16 v[16:19], v[238:241], v[204:207], v[16:19]
	v_add_u32_e32 v225, 0x6800, v162
	ds_read2_b64 v[238:241], v225 offset1:4
	s_waitcnt lgkmcnt(4)
	v_mfma_f32_16x16x32_f16 v[76:79], v[242:245], v[196:199], v[76:79]
	v_mfma_f32_16x16x32_f16 v[12:15], v[242:245], v[208:211], v[12:15]
	ds_read2_b64 v[242:245], v225 offset0:8 offset1:12
	s_waitcnt lgkmcnt(4)
	v_mfma_f32_16x16x32_f16 v[76:79], v[246:249], v[200:203], v[76:79]
	v_mfma_f32_16x16x32_f16 v[12:15], v[246:249], v[204:207], v[12:15]
	v_add_u32_e32 v222, 0x7000, v162
	ds_read2_b64 v[246:249], v222 offset0:32 offset1:36
	s_waitcnt lgkmcnt(4)
	v_mfma_f32_16x16x32_f16 v[72:75], v[226:229], v[196:199], v[72:75]
	v_mfma_f32_16x16x32_f16 v[8:11], v[226:229], v[208:211], v[8:11]
	ds_read2_b64 v[226:229], v222 offset0:40 offset1:44
	s_waitcnt lgkmcnt(4)
	v_mfma_f32_16x16x32_f16 v[72:75], v[234:237], v[200:203], v[72:75]
	v_mfma_f32_16x16x32_f16 v[8:11], v[234:237], v[204:207], v[8:11]
	v_add_u32_e32 v223, 0x7800, v162
	ds_read2_b64 v[234:237], v223 offset0:64 offset1:68
	s_waitcnt lgkmcnt(4)
	v_mfma_f32_16x16x32_f16 v[68:71], v[238:241], v[196:199], v[68:71]
	v_mfma_f32_16x16x32_f16 v[4:7], v[238:241], v[208:211], v[4:7]
	ds_read2_b64 v[238:241], v223 offset0:72 offset1:76
	s_waitcnt lgkmcnt(4)
	v_mfma_f32_16x16x32_f16 v[68:71], v[242:245], v[200:203], v[68:71]
	v_mfma_f32_16x16x32_f16 v[4:7], v[242:245], v[204:207], v[4:7]
	v_add_u32_e32 v224, 0x8000, v162
	ds_read2_b64 v[242:245], v224 offset0:96 offset1:100
	s_waitcnt lgkmcnt(4)
	v_mfma_f32_16x16x32_f16 v[96:99], v[246:249], v[196:199], v[96:99]
	v_mfma_f32_16x16x32_f16 v[32:35], v[246:249], v[208:211], v[32:35]
	ds_read2_b64 v[246:249], v224 offset0:104 offset1:108
	s_waitcnt lgkmcnt(4)
	v_mfma_f32_16x16x32_f16 v[96:99], v[226:229], v[200:203], v[96:99]
	v_mfma_f32_16x16x32_f16 v[32:35], v[226:229], v[204:207], v[32:35]
	s_waitcnt lgkmcnt(3)
	v_mfma_f32_16x16x32_f16 v[88:91], v[234:237], v[196:199], v[88:91]
	v_mfma_f32_16x16x32_f16 v[28:31], v[234:237], v[208:211], v[28:31]
	s_waitcnt lgkmcnt(2)
	v_mfma_f32_16x16x32_f16 v[88:91], v[238:241], v[200:203], v[88:91]
	v_mfma_f32_16x16x32_f16 v[28:31], v[238:241], v[204:207], v[28:31]
	s_waitcnt lgkmcnt(1)
	v_mfma_f32_16x16x32_f16 v[84:87], v[242:245], v[196:199], v[84:87]
	v_mfma_f32_16x16x32_f16 v[24:27], v[242:245], v[208:211], v[24:27]
	s_waitcnt lgkmcnt(0)
	v_mfma_f32_16x16x32_f16 v[84:87], v[246:249], v[200:203], v[84:87]
	v_mfma_f32_16x16x32_f16 v[24:27], v[246:249], v[204:207], v[24:27]
	s_cbranch_vccnz .LBB0_249
	s_xor_b32 s0, s12, 1
	s_mul_i32 s0, s0, 0x8c00
	s_add_i32 s0, s0, 0
	v_add3_u32 v162, s0, v153, v152
	s_waitcnt vmcnt(3)
	ds_write_b128 v162, v[100:103]
	s_waitcnt vmcnt(2)
	ds_write_b128 v162, v[104:107] offset:8704
	v_add3_u32 v162, s0, v183, v156
	s_waitcnt vmcnt(1)
	ds_write_b128 v162, v[108:111] offset:17408
	s_waitcnt vmcnt(0)
	ds_write_b128 v162, v[112:115] offset:26624
	s_branch .LBB0_249
